# attention: static priority of waves 0-3 raised to 3 instead of 1
# baseline (speedup 1.0000x reference)
; __device__ __forceinline__ void attn_phase(const Params& p, LAS unsigned char* lds) {
;     ...
;     int tid_ = threadIdx.x; asm volatile("" : "+v"(tid_));
;     const int tid = tid_, lane = tid & 63, wid = tid >> 6, c = lane & 31, hi = lane >> 5;
;     const float NEG = -__builtin_inff();
;     const int srow = tid >> 3, ssub = tid & 7;
;     const int G_ = gridDim.x, vcu = (G_ % 8 == 0) ? (int)(blockIdx.x & 7) * (G_ >> 3) + (int)(blockIdx.x >> 3) : (int)blockIdx.x;
.LBB0_630:
	s_or_b64 exec, exec, s[0:1]
	v_readfirstlane_b32 s99, v201
	s_nop 3
	s_lshr_b32 s99, s99, 8
	s_cmp_eq_u32 s99, 0
	s_cbranch_scc0 .Lprio4_skip
	s_setprio 3
